# strategy 2: phase B2 k-type epilogue, the norm-gain and cos/sin loads issued before the k loop instead of six load/vmcnt(0) steps
# baseline (speedup 1.0000x reference)
; DI void phaseB2(const Params& p0, int layer, unsigned char* lds) {
;     ...
;   for (int wi = blockIdx.x * 2 + w; wi < 32 * 16; wi += gridDim.x * 2) {
;     const int item = wi >> 4, r16 = wi & 15, kv = item & 1, pair = item >> 1;
;     const int row = r16 * 16 + qi;
;     const bf16_t* W2 = p.w2t() + (long)kv * 64 * 256;
;     const float* hp = p.hpre() + ((long)item * 256 + row) * 256 + quad * 8;
;     f32x4 o[4];
; #pragma unroll
;     for (int dt = 0; dt < 4; ++dt) o[dt] = (f32x4){0.f, 0.f, 0.f, 0.f};
;     ...
;       const float* g = p.kng() + (layer * 3 + 0) * 64;
;       const int b = bg >> 1, c = (r16 & 7) * 16 + qi;
;       float ss = 0.f;
; #pragma unroll
;       for (int dt = 0; dt < 4; ++dt) ss += o[dt][0] * o[dt][0] + o[dt][1] * o[dt][1] + o[dt][2] * o[dt][2] + o[dt][3] * o[dt][3];
;       ss += __shfl_xor(ss, 16); ss += __shfl_xor(ss, 32);
;       const float rn = rsqrtf(ss * (1.f / 64.f) + NORM_EPS);
; #pragma unroll
;       for (int dt = 0; dt < 4; ++dt) { const f32x4 gg = *(const f32x4*)(g + dt * 16 + quad * 4); o[dt] = o[dt] * rn * gg; }
; #pragma unroll
;       for (int dt = 0; dt < 2; ++dt) {
;         const long ti = ((long)b * 128 + c) * 32 + dt * 16 + quad * 4;
;         const f32x4 cs = *(const f32x4*)(p.cosC() + ti), sn = *(const f32x4*)(p.sinC() + ti);
.LBB0_628:
	v_ashrrev_i32_e32 v36, 4, v29
	v_and_b32_e32 v0, 15, v46
	v_ashrrev_i32_e32 v37, 31, v36
	v_lshlrev_b32_e32 v4, 2, v26
	v_lshlrev_b32_e32 v0, 14, v0
	v_lshlrev_b64 v[2:3], 18, v[36:37]
	v_and_b32_e32 v5, 1, v36
	v_or3_b32 v2, v0, v4, v2
	v_lshl_add_u64 v[38:39], v[32:33], 0, v[2:3]
	v_lshlrev_b32_e32 v0, 15, v5
	v_mov_b32_e32 v2, 0
	v_lshl_add_u32 v37, v5, 10, v45
	v_cmp_eq_u32_e64 s[8:9], 1, v5
	v_lshl_add_u64 v[40:41], v[34:35], 0, v[0:1]
	s_mov_b32 s27, 0
	v_mov_b32_e32 v3, v2
	v_mov_b32_e32 v4, v2
	v_mov_b32_e32 v5, v2
	v_mov_b32_e32 v14, v2
	v_mov_b32_e32 v15, v2
	v_mov_b32_e32 v16, v2
	v_mov_b32_e32 v17, v2
	v_mov_b32_e32 v10, v2
	v_mov_b32_e32 v11, v2
	v_mov_b32_e32 v12, v2
	v_mov_b32_e32 v13, v2
	v_mov_b32_e32 v6, v2
	v_mov_b32_e32 v7, v2
	v_mov_b32_e32 v8, v2
	v_mov_b32_e32 v9, v2
	s_cmp_lg_u64 s[8:9], 0
	s_cbranch_scc1 .Lmy_b2e_skip
	global_load_dwordx4 v[164:167], v[30:31], off
	global_load_dwordx4 v[168:171], v[30:31], off offset:64
	global_load_dwordx4 v[172:175], v[30:31], off offset:128
	global_load_dwordx4 v[176:179], v[30:31], off offset:192
	v_lshlrev_b32_e32 v196, 4, v29
	v_and_b32_e32 v196, 0x70, v196
	v_or_b32_e32 v196, v196, v44
	v_ashrrev_i32_e32 v198, 5, v29
	v_ashrrev_i32_e32 v199, 31, v198
	v_lshlrev_b64 v[198:199], 12, v[198:199]
	v_lshl_or_b32 v196, v196, 5, v198
	v_or_b32_e32 v198, v196, v28
	v_lshlrev_b64 v[198:199], 2, v[198:199]
	v_lshl_add_u64 v[196:197], s[0:1], 0, v[198:199]
	global_load_dwordx4 v[180:183], v[196:197], off
	v_lshl_add_u64 v[196:197], s[14:15], 0, v[198:199]
	global_load_dwordx4 v[184:187], v[196:197], off
	v_or_b32_e32 v198, 64, v198
	v_lshl_add_u64 v[196:197], s[0:1], 0, v[198:199]
	global_load_dwordx4 v[188:191], v[196:197], off
	v_lshl_add_u64 v[196:197], s[14:15], 0, v[198:199]
	global_load_dwordx4 v[192:195], v[196:197], off
.Lmy_b2e_skip:
	s_branch .LBB0_630
.LBB0_629:
	s_or_b64 exec, exec, s[38:39]
	s_addk_i32 s27, 0x80
	v_lshl_add_u64 v[38:39], v[38:39], 0, s[6:7]
	s_cmpk_eq_i32 s27, 0x400
	v_lshl_add_u64 v[40:41], v[40:41], 0, 64
	s_cbranch_scc1 .LBB0_646

; DI unsigned pk2(float lo, float hi) { f32x2 v = {lo, hi}; bf16x2_t b = __builtin_convertvector(v, bf16x2_t); return __builtin_bit_cast(unsigned, b); }
; DI void phaseB2(const Params& p0, int layer, unsigned char* lds) {
;     ...
;     if (kv == 0) {
;       const float* g = p.kng() + (layer * 3 + 0) * 64;
;       const int b = bg >> 1, c = (r16 & 7) * 16 + qi;
;       float ss = 0.f;
; #pragma unroll
;       for (int dt = 0; dt < 4; ++dt) ss += o[dt][0] * o[dt][0] + o[dt][1] * o[dt][1] + o[dt][2] * o[dt][2] + o[dt][3] * o[dt][3];
;       ss += __shfl_xor(ss, 16); ss += __shfl_xor(ss, 32);
;       const float rn = rsqrtf(ss * (1.f / 64.f) + NORM_EPS);
; #pragma unroll
;       for (int dt = 0; dt < 4; ++dt) { const f32x4 gg = *(const f32x4*)(g + dt * 16 + quad * 4); o[dt] = o[dt] * rn * gg; }
; #pragma unroll
;       for (int dt = 0; dt < 2; ++dt) {
;         const long ti = ((long)b * 128 + c) * 32 + dt * 16 + quad * 4;
;         const f32x4 cs = *(const f32x4*)(p.cosC() + ti), sn = *(const f32x4*)(p.sinC() + ti);
;         const f32x4 x1 = o[dt], x2 = o[dt + 2];
;         o[dt] = x1 * cs - x2 * sn; o[dt + 2] = x2 * cs + x1 * sn;
;       }
;       bf16_t* dst = p.kc() + ((long)bg * 128 + c) * 64 + quad * 4;
; #pragma unroll
;       for (int dt = 0; dt < 4; ++dt) {
;         u32x2 ov = (u32x2){pk2(o[dt][0], o[dt][1]), pk2(o[dt][2], o[dt][3])};
;         if (c >= NCMP) ov = (u32x2){0u, 0u};
;         *(u32x2*)(dst + dt * 16) = ov;
;       }
.LBB0_648:
	s_andn2_saveexec_b64 s[8:9], s[38:39]
	s_cbranch_execz .LBB0_627
	s_waitcnt vmcnt(0)
	v_mov_b32_e32 v22, v15
	v_mov_b32_e32 v23, v11
	v_mov_b32_e32 v20, v14
	v_mov_b32_e32 v21, v10
	v_pk_mul_f32 v[22:23], v[22:23], v[22:23]
	v_mov_b32_e32 v24, v7
	v_pk_fma_f32 v[20:21], v[20:21], v[20:21], v[22:23]
	v_mov_b32_e32 v22, v16
	v_mov_b32_e32 v23, v12
	v_pk_fma_f32 v[20:21], v[22:23], v[22:23], v[20:21]
	v_mov_b32_e32 v22, v17
	v_mov_b32_e32 v23, v13
	v_mov_b32_e32 v25, v3
	v_pk_fma_f32 v[20:21], v[22:23], v[22:23], v[20:21]
	v_mov_b32_e32 v22, v6
	v_mov_b32_e32 v23, v2
	v_pk_mul_f32 v[24:25], v[24:25], v[24:25]
	v_add_f32_e32 v20, v20, v21
	v_pk_fma_f32 v[22:23], v[22:23], v[22:23], v[24:25]
	v_mov_b32_e32 v24, v8
	v_mov_b32_e32 v25, v4
	v_pk_fma_f32 v[22:23], v[24:25], v[24:25], v[22:23]
	v_mov_b32_e32 v24, v9
	v_mov_b32_e32 v25, v5
	v_pk_fma_f32 v[22:23], v[24:25], v[24:25], v[22:23]
	v_xor_b32_e32 v21, 16, v228
	v_add_f32_e32 v20, v20, v22
	v_and_b32_e32 v22, 64, v228
	v_add_u32_e32 v22, 64, v22
	v_cmp_lt_i32_e32 vcc, v21, v22
	v_add_f32_e32 v20, v20, v23
	s_mov_b32 s24, 0x800000
	v_cndmask_b32_e32 v21, v228, v21, vcc
	v_lshlrev_b32_e32 v21, 2, v21
	ds_bpermute_b32 v21, v21, v20
	v_ashrrev_i32_e32 v24, 5, v29
	v_ashrrev_i32_e32 v25, 31, v24
	v_or_b32_e32 v47, v0, v44
	s_movk_i32 s27, 0x7f
	s_waitcnt lgkmcnt(0)
	v_add_f32_e32 v20, v20, v21
	v_xor_b32_e32 v21, 32, v228
	v_cmp_lt_i32_e32 vcc, v21, v22
	s_nop 1
	v_cndmask_b32_e32 v21, v228, v21, vcc
	v_lshlrev_b32_e32 v21, 2, v21
	ds_bpermute_b32 v21, v21, v20
	s_waitcnt lgkmcnt(0)
	v_add_f32_e32 v20, v20, v21
	v_fmamk_f32 v20, v20, 0x3c800000, v214
	v_cmp_gt_f32_e32 vcc, s24, v20
	v_mul_f32_e32 v21, 0x4b800000, v20
	s_nop 0
	v_cndmask_b32_e32 v20, v20, v21, vcc
	v_rsq_f32_e32 v20, v20
	s_nop 0
	v_mul_f32_e32 v21, 0x45800000, v20
	v_cndmask_b32_e32 v36, v20, v21, vcc
	v_mov_b64_e32 v[20:21], v[164:165]
	v_mov_b64_e32 v[22:23], v[166:167]
	v_pk_mul_f32 v[16:17], v[16:17], v[36:37] op_sel_hi:[1,0]
	v_pk_mul_f32 v[14:15], v[14:15], v[36:37] op_sel_hi:[1,0]
	v_pk_mul_f32 v[12:13], v[12:13], v[36:37] op_sel_hi:[1,0]
	v_pk_mul_f32 v[10:11], v[10:11], v[36:37] op_sel_hi:[1,0]
	v_pk_mul_f32 v[6:7], v[6:7], v[36:37] op_sel_hi:[1,0]
	v_pk_mul_f32 v[8:9], v[8:9], v[36:37] op_sel_hi:[1,0]
	v_pk_mul_f32 v[2:3], v[2:3], v[36:37] op_sel_hi:[1,0]
	v_pk_mul_f32 v[4:5], v[4:5], v[36:37] op_sel_hi:[1,0]
	v_cmp_eq_u32_e32 vcc, s27, v47
	v_pk_mul_f32 v[20:21], v[20:21], v[14:15]
	v_pk_mul_f32 v[22:23], v[22:23], v[16:17]
	v_mov_b64_e32 v[14:15], v[168:169]
	v_mov_b64_e32 v[16:17], v[170:171]
	v_pk_mul_f32 v[10:11], v[14:15], v[10:11]
	v_pk_mul_f32 v[12:13], v[16:17], v[12:13]
	v_mov_b64_e32 v[14:15], v[172:173]
	v_mov_b64_e32 v[16:17], v[174:175]
	v_pk_mul_f32 v[38:39], v[16:17], v[8:9]
	v_pk_mul_f32 v[40:41], v[14:15], v[6:7]
	v_mov_b64_e32 v[6:7], v[176:177]
	v_mov_b64_e32 v[8:9], v[178:179]
	v_pk_mul_f32 v[16:17], v[6:7], v[2:3]
	v_lshlrev_b64 v[2:3], 12, v[24:25]
	v_lshl_or_b32 v0, v47, 5, v2
	v_or_b32_e32 v2, v0, v28
	v_lshlrev_b64 v[42:43], 2, v[2:3]
	v_lshl_add_u64 v[2:3], s[0:1], 0, v[42:43]
	v_lshl_add_u64 v[6:7], s[14:15], 0, v[42:43]
	v_pk_mul_f32 v[14:15], v[8:9], v[4:5]
	v_mov_b64_e32 v[2:3], v[180:181]
	v_mov_b64_e32 v[4:5], v[182:183]
	v_or_b32_e32 v42, 64, v42
	v_mov_b64_e32 v[6:7], v[184:185]
	v_mov_b64_e32 v[8:9], v[186:187]
	v_lshlrev_b32_e32 v0, 7, v47
	v_pk_mul_f32 v[36:37], v[6:7], v[40:41]
	v_pk_mul_f32 v[24:25], v[8:9], v[38:39]
	v_pk_mul_f32 v[6:7], v[6:7], v[20:21]
	v_pk_fma_f32 v[24:25], v[4:5], v[22:23], v[24:25] neg_lo:[0,0,1] neg_hi:[0,0,1]
	v_pk_fma_f32 v[36:37], v[2:3], v[20:21], v[36:37] neg_lo:[0,0,1] neg_hi:[0,0,1]
	v_pk_mul_f32 v[8:9], v[8:9], v[22:23]
	v_pk_fma_f32 v[22:23], v[2:3], v[40:41], v[6:7]
	v_lshl_add_u64 v[2:3], s[0:1], 0, v[42:43]
	v_lshl_add_u64 v[6:7], s[14:15], 0, v[42:43]
	v_pk_fma_f32 v[20:21], v[4:5], v[38:39], v[8:9]
	v_mov_b64_e32 v[2:3], v[188:189]
	v_mov_b64_e32 v[4:5], v[190:191]
	s_nop 0
	v_mov_b64_e32 v[6:7], v[192:193]
	v_mov_b64_e32 v[8:9], v[194:195]
	v_pk_mul_f32 v[38:39], v[6:7], v[16:17]
	v_pk_mul_f32 v[6:7], v[6:7], v[10:11]
	v_pk_fma_f32 v[38:39], v[2:3], v[10:11], v[38:39] neg_lo:[0,0,1] neg_hi:[0,0,1]
	v_pk_fma_f32 v[2:3], v[2:3], v[16:17], v[6:7]
	v_lshlrev_b64 v[6:7], 14, v[18:19]
	v_lshl_add_u64 v[6:7], s[16:17], 0, v[6:7]
	v_pk_mul_f32 v[40:41], v[8:9], v[14:15]
	v_pk_mul_f32 v[8:9], v[8:9], v[12:13]
	v_lshl_add_u64 v[6:7], v[6:7], 0, v[0:1]
	v_lshlrev_b32_e32 v0, 1, v28
	v_pk_fma_f32 v[40:41], v[4:5], v[12:13], v[40:41] neg_lo:[0,0,1] neg_hi:[0,0,1]
	v_pk_fma_f32 v[4:5], v[4:5], v[14:15], v[8:9]
	v_lshl_add_u64 v[6:7], v[6:7], 0, v[0:1]
	v_cvt_pk_bf16_f32 v0, v36, v37
	v_cvt_pk_bf16_f32 v8, v24, v25
	v_cndmask_b32_e64 v9, v8, 0, vcc
	v_cndmask_b32_e64 v8, v0, 0, vcc
	global_store_dwordx2 v[6:7], v[8:9], off
	v_cvt_pk_bf16_f32 v0, v38, v39
	v_cvt_pk_bf16_f32 v8, v40, v41
	v_cndmask_b32_e64 v9, v8, 0, vcc
	v_cndmask_b32_e64 v8, v0, 0, vcc
	global_store_dwordx2 v[6:7], v[8:9], off offset:32
	v_cvt_pk_bf16_f32 v0, v22, v23
	v_cvt_pk_bf16_f32 v8, v20, v21
	v_cndmask_b32_e64 v9, v8, 0, vcc
	v_cndmask_b32_e64 v8, v0, 0, vcc
	v_cvt_pk_bf16_f32 v0, v2, v3
	v_cvt_pk_bf16_f32 v2, v4, v5
	v_cndmask_b32_e64 v3, v2, 0, vcc
	v_cndmask_b32_e64 v2, v0, 0, vcc
	global_store_dwordx2 v[6:7], v[8:9], off offset:64
	global_store_dwordx2 v[6:7], v[2:3], off offset:96
	s_branch .LBB0_627
